# S single-group step without causal mask: softmax VALU of one 32-key half issued in the gaps between the MFMAs of the other half (QK of keys 32..63, PV of keys 0..31)
# speedup vs baseline: 1.0028x; 1.0028x over previous
.Lsb16_g0only_0:
	s_cmp_eq_u32 s76, s72
	s_cbranch_scc1 .Lsb16_g0m_0
	v_subrev_u32_e32 v146, s94, v236
	v_lshrrev_b32_e64 v146, v146, s77
	v_and_b32_e32 v146, 1, v146
	v_cmp_ne_u32_e32 vcc, 0, v146
	s_nop 1
	v_cndmask_b32_e32 v146, v213, v100, vcc
	s_waitcnt lgkmcnt(9)
	v_mfma_f32_16x16x32_bf16 v[34:37], v[50:53], v[66:69], 0
	s_waitcnt lgkmcnt(8)
	v_mfma_f32_16x16x32_bf16 v[34:37], v[54:57], v[70:73], v[34:37]
	ds_read_b128 v[50:53], v234 offset:6912
	ds_read_b128 v[54:57], v234 offset:6976
	s_waitcnt lgkmcnt(9)
	v_mfma_f32_16x16x32_bf16 v[38:41], v[58:61], v[66:69], 0
	s_waitcnt lgkmcnt(8)
	v_mfma_f32_16x16x32_bf16 v[38:41], v[62:65], v[70:73], v[38:41]
	ds_read_b128 v[58:61], v234 offset:9216
	ds_read_b128 v[62:65], v234 offset:11520
	s_waitcnt lgkmcnt(9)
	v_mfma_f32_16x16x32_bf16 v[42:45], v[138:141], v[66:69], 0
	v_fma_f32 v34, v34, s48, v146
	v_fma_f32 v35, v35, s48, v146
	s_waitcnt lgkmcnt(8)
	v_mfma_f32_16x16x32_bf16 v[42:45], v[142:145], v[70:73], v[42:45]
	v_fma_f32 v36, v36, s48, v146
	v_fma_f32 v37, v37, s48, v146
	s_waitcnt lgkmcnt(3)
	v_mfma_f32_16x16x32_bf16 v[46:49], v[50:53], v[66:69], 0
	v_fma_f32 v38, v38, s48, v146
	v_fma_f32 v39, v39, s48, v146
	s_waitcnt lgkmcnt(2)
	v_mfma_f32_16x16x32_bf16 v[46:49], v[54:57], v[70:73], v[46:49]
	v_fma_f32 v40, v40, s48, v146
	v_fma_f32 v41, v41, s48, v146
	ds_read_b128 v[50:53], v234 offset:13824
	ds_read_b128 v[54:57], v234 offset:16128
	v_exp_f32_e32 v34, v34
	v_exp_f32_e32 v35, v35
	v_exp_f32_e32 v36, v36
	v_exp_f32_e32 v37, v37
	v_exp_f32_e32 v38, v38
	v_exp_f32_e32 v39, v39
	v_exp_f32_e32 v40, v40
	v_exp_f32_e32 v41, v41
	v_add_f32_e32 v142, v34, v35
	v_add_f32_e32 v143, v36, v37
	v_add_f32_e32 v142, v142, v38
	v_add_f32_e32 v143, v143, v39
	v_add_f32_e32 v142, v142, v40
	v_add_f32_e32 v143, v143, v41
	v_add_f32_e32 v142, v142, v143
	v_add_f32_e32 v129, v129, v142
	v_cvt_pk_bf16_f32 v138, v34, v35
	v_cvt_pk_bf16_f32 v139, v36, v37
	v_cvt_pk_bf16_f32 v140, v38, v39
	v_cvt_pk_bf16_f32 v141, v40, v41
	s_nop 0
	s_waitcnt lgkmcnt(3)
	v_mfma_f32_16x16x32_bf16 v[2:5], v[58:61], v[138:141], v[2:5]
	v_fma_f32 v42, v42, s48, v146
	v_fma_f32 v43, v43, s48, v146
	ds_read_b128 v[58:61], v234 offset:9280
	s_waitcnt lgkmcnt(3)
	v_mfma_f32_16x16x32_bf16 v[6:9], v[62:65], v[138:141], v[6:9]
	v_fma_f32 v44, v44, s48, v146
	v_fma_f32 v45, v45, s48, v146
	ds_read_b128 v[62:65], v234 offset:11584
	s_waitcnt lgkmcnt(3)
	v_mfma_f32_16x16x32_bf16 v[10:13], v[50:53], v[138:141], v[10:13]
	v_fma_f32 v46, v46, s48, v146
	v_fma_f32 v47, v47, s48, v146
	ds_read_b128 v[50:53], v234 offset:13888
	s_waitcnt lgkmcnt(3)
	v_mfma_f32_16x16x32_bf16 v[14:17], v[54:57], v[138:141], v[14:17]
	v_fma_f32 v48, v48, s48, v146
	v_fma_f32 v49, v49, s48, v146
	ds_read_b128 v[54:57], v234 offset:16192
	v_exp_f32_e32 v42, v42
	v_exp_f32_e32 v43, v43
	v_exp_f32_e32 v44, v44
	v_exp_f32_e32 v45, v45
	v_exp_f32_e32 v46, v46
	v_exp_f32_e32 v47, v47
	v_exp_f32_e32 v48, v48
	v_exp_f32_e32 v49, v49
	v_add_f32_e32 v34, v42, v43
	v_add_f32_e32 v35, v44, v45
	v_add_f32_e32 v34, v34, v46
	v_add_f32_e32 v35, v35, v47
	v_add_f32_e32 v34, v34, v48
	v_add_f32_e32 v35, v35, v49
	v_add_f32_e32 v34, v34, v35
	v_add_f32_e32 v129, v129, v34
	v_cvt_pk_bf16_f32 v142, v42, v43
	v_cvt_pk_bf16_f32 v143, v44, v45
	v_cvt_pk_bf16_f32 v144, v46, v47
	v_cvt_pk_bf16_f32 v145, v48, v49
	s_nop 0
	s_waitcnt lgkmcnt(3)
	v_mfma_f32_16x16x32_bf16 v[2:5], v[58:61], v[142:145], v[2:5]
	s_waitcnt lgkmcnt(2)
	v_mfma_f32_16x16x32_bf16 v[6:9], v[62:65], v[142:145], v[6:9]
	s_waitcnt lgkmcnt(1)
	v_mfma_f32_16x16x32_bf16 v[10:13], v[50:53], v[142:145], v[10:13]
	s_waitcnt lgkmcnt(0)
	v_mfma_f32_16x16x32_bf16 v[14:17], v[54:57], v[142:145], v[14:17]
	s_branch .Lsb16_end_0

.Lsb16_g1only_0:
	s_cmp_eq_u32 s76, s72
	s_cbranch_scc1 .Lsb16_g1m_0
	v_subrev_u32_e32 v146, s94, v236
	v_add_u32_e32 v146, 2, v146
	v_lshrrev_b32_e64 v146, v146, s77
	v_and_b32_e32 v146, 1, v146
	v_cmp_ne_u32_e32 vcc, 0, v146
	s_nop 1
	v_cndmask_b32_e32 v146, v213, v100, vcc
	s_waitcnt lgkmcnt(9)
	v_mfma_f32_16x16x32_bf16 v[34:37], v[50:53], v[74:77], 0
	s_waitcnt lgkmcnt(8)
	v_mfma_f32_16x16x32_bf16 v[34:37], v[54:57], v[78:81], v[34:37]
	ds_read_b128 v[50:53], v234 offset:6912
	ds_read_b128 v[54:57], v234 offset:6976
	s_waitcnt lgkmcnt(9)
	v_mfma_f32_16x16x32_bf16 v[38:41], v[58:61], v[74:77], 0
	s_waitcnt lgkmcnt(8)
	v_mfma_f32_16x16x32_bf16 v[38:41], v[62:65], v[78:81], v[38:41]
	ds_read_b128 v[58:61], v234 offset:9216
	ds_read_b128 v[62:65], v234 offset:11520
	s_waitcnt lgkmcnt(9)
	v_mfma_f32_16x16x32_bf16 v[42:45], v[138:141], v[74:77], 0
	v_fma_f32 v34, v34, s48, v146
	v_fma_f32 v35, v35, s48, v146
	s_waitcnt lgkmcnt(8)
	v_mfma_f32_16x16x32_bf16 v[42:45], v[142:145], v[78:81], v[42:45]
	v_fma_f32 v36, v36, s48, v146
	v_fma_f32 v37, v37, s48, v146
	s_waitcnt lgkmcnt(3)
	v_mfma_f32_16x16x32_bf16 v[46:49], v[50:53], v[74:77], 0
	v_fma_f32 v38, v38, s48, v146
	v_fma_f32 v39, v39, s48, v146
	s_waitcnt lgkmcnt(2)
	v_mfma_f32_16x16x32_bf16 v[46:49], v[54:57], v[78:81], v[46:49]
	v_fma_f32 v40, v40, s48, v146
	v_fma_f32 v41, v41, s48, v146
	ds_read_b128 v[50:53], v234 offset:13824
	ds_read_b128 v[54:57], v234 offset:16128
	v_exp_f32_e32 v34, v34
	v_exp_f32_e32 v35, v35
	v_exp_f32_e32 v36, v36
	v_exp_f32_e32 v37, v37
	v_exp_f32_e32 v38, v38
	v_exp_f32_e32 v39, v39
	v_exp_f32_e32 v40, v40
	v_exp_f32_e32 v41, v41
	v_add_f32_e32 v142, v34, v35
	v_add_f32_e32 v143, v36, v37
	v_add_f32_e32 v142, v142, v38
	v_add_f32_e32 v143, v143, v39
	v_add_f32_e32 v142, v142, v40
	v_add_f32_e32 v143, v143, v41
	v_add_f32_e32 v142, v142, v143
	v_add_f32_e32 v235, v235, v142
	v_cvt_pk_bf16_f32 v138, v34, v35
	v_cvt_pk_bf16_f32 v139, v36, v37
	v_cvt_pk_bf16_f32 v140, v38, v39
	v_cvt_pk_bf16_f32 v141, v40, v41
	s_nop 0
	s_waitcnt lgkmcnt(3)
	v_mfma_f32_16x16x32_bf16 v[18:21], v[58:61], v[138:141], v[18:21]
	v_fma_f32 v42, v42, s48, v146
	v_fma_f32 v43, v43, s48, v146
	ds_read_b128 v[58:61], v234 offset:9280
	s_waitcnt lgkmcnt(3)
	v_mfma_f32_16x16x32_bf16 v[22:25], v[62:65], v[138:141], v[22:25]
	v_fma_f32 v44, v44, s48, v146
	v_fma_f32 v45, v45, s48, v146
	ds_read_b128 v[62:65], v234 offset:11584
	s_waitcnt lgkmcnt(3)
	v_mfma_f32_16x16x32_bf16 v[26:29], v[50:53], v[138:141], v[26:29]
	v_fma_f32 v46, v46, s48, v146
	v_fma_f32 v47, v47, s48, v146
	ds_read_b128 v[50:53], v234 offset:13888
	s_waitcnt lgkmcnt(3)
	v_mfma_f32_16x16x32_bf16 v[30:33], v[54:57], v[138:141], v[30:33]
	v_fma_f32 v48, v48, s48, v146
	v_fma_f32 v49, v49, s48, v146
	ds_read_b128 v[54:57], v234 offset:16192
	v_exp_f32_e32 v42, v42
	v_exp_f32_e32 v43, v43
	v_exp_f32_e32 v44, v44
	v_exp_f32_e32 v45, v45
	v_exp_f32_e32 v46, v46
	v_exp_f32_e32 v47, v47
	v_exp_f32_e32 v48, v48
	v_exp_f32_e32 v49, v49
	v_add_f32_e32 v34, v42, v43
	v_add_f32_e32 v35, v44, v45
	v_add_f32_e32 v34, v34, v46
	v_add_f32_e32 v35, v35, v47
	v_add_f32_e32 v34, v34, v48
	v_add_f32_e32 v35, v35, v49
	v_add_f32_e32 v34, v34, v35
	v_add_f32_e32 v235, v235, v34
	v_cvt_pk_bf16_f32 v142, v42, v43
	v_cvt_pk_bf16_f32 v143, v44, v45
	v_cvt_pk_bf16_f32 v144, v46, v47
	v_cvt_pk_bf16_f32 v145, v48, v49
	s_nop 0
	s_waitcnt lgkmcnt(3)
	v_mfma_f32_16x16x32_bf16 v[18:21], v[58:61], v[142:145], v[18:21]
	s_waitcnt lgkmcnt(2)
	v_mfma_f32_16x16x32_bf16 v[22:25], v[62:65], v[142:145], v[22:25]
	s_waitcnt lgkmcnt(1)
	v_mfma_f32_16x16x32_bf16 v[26:29], v[50:53], v[142:145], v[26:29]
	s_waitcnt lgkmcnt(0)
	v_mfma_f32_16x16x32_bf16 v[30:33], v[54:57], v[142:145], v[30:33]
	s_branch .Lsb16_end_0

.Lsb16_g0only_1:
	s_cmp_eq_u32 s76, s72
	s_cbranch_scc1 .Lsb16_g0m_1
	v_subrev_u32_e32 v146, s94, v236
	v_lshrrev_b32_e64 v146, v146, s77
	v_and_b32_e32 v146, 1, v146
	v_cmp_ne_u32_e32 vcc, 0, v146
	s_nop 1
	v_cndmask_b32_e32 v146, v213, v100, vcc
	s_waitcnt lgkmcnt(9)
	v_mfma_f32_16x16x32_bf16 v[34:37], v[50:53], v[66:69], 0
	s_waitcnt lgkmcnt(8)
	v_mfma_f32_16x16x32_bf16 v[34:37], v[54:57], v[70:73], v[34:37]
	ds_read_b128 v[50:53], v234 offset:25344
	ds_read_b128 v[54:57], v234 offset:25408
	s_waitcnt lgkmcnt(9)
	v_mfma_f32_16x16x32_bf16 v[38:41], v[58:61], v[66:69], 0
	s_waitcnt lgkmcnt(8)
	v_mfma_f32_16x16x32_bf16 v[38:41], v[62:65], v[70:73], v[38:41]
	ds_read_b128 v[58:61], v234 offset:27648
	ds_read_b128 v[62:65], v234 offset:29952
	s_waitcnt lgkmcnt(9)
	v_mfma_f32_16x16x32_bf16 v[42:45], v[138:141], v[66:69], 0
	v_fma_f32 v34, v34, s48, v146
	v_fma_f32 v35, v35, s48, v146
	s_waitcnt lgkmcnt(8)
	v_mfma_f32_16x16x32_bf16 v[42:45], v[142:145], v[70:73], v[42:45]
	v_fma_f32 v36, v36, s48, v146
	v_fma_f32 v37, v37, s48, v146
	s_waitcnt lgkmcnt(3)
	v_mfma_f32_16x16x32_bf16 v[46:49], v[50:53], v[66:69], 0
	v_fma_f32 v38, v38, s48, v146
	v_fma_f32 v39, v39, s48, v146
	s_waitcnt lgkmcnt(2)
	v_mfma_f32_16x16x32_bf16 v[46:49], v[54:57], v[70:73], v[46:49]
	v_fma_f32 v40, v40, s48, v146
	v_fma_f32 v41, v41, s48, v146
	ds_read_b128 v[50:53], v234 offset:32256
	ds_read_b128 v[54:57], v234 offset:34560
	v_exp_f32_e32 v34, v34
	v_exp_f32_e32 v35, v35
	v_exp_f32_e32 v36, v36
	v_exp_f32_e32 v37, v37
	v_exp_f32_e32 v38, v38
	v_exp_f32_e32 v39, v39
	v_exp_f32_e32 v40, v40
	v_exp_f32_e32 v41, v41
	v_add_f32_e32 v142, v34, v35
	v_add_f32_e32 v143, v36, v37
	v_add_f32_e32 v142, v142, v38
	v_add_f32_e32 v143, v143, v39
	v_add_f32_e32 v142, v142, v40
	v_add_f32_e32 v143, v143, v41
	v_add_f32_e32 v142, v142, v143
	v_add_f32_e32 v129, v129, v142
	v_cvt_pk_bf16_f32 v138, v34, v35
	v_cvt_pk_bf16_f32 v139, v36, v37
	v_cvt_pk_bf16_f32 v140, v38, v39
	v_cvt_pk_bf16_f32 v141, v40, v41
	s_nop 0
	s_waitcnt lgkmcnt(3)
	v_mfma_f32_16x16x32_bf16 v[2:5], v[58:61], v[138:141], v[2:5]
	v_fma_f32 v42, v42, s48, v146
	v_fma_f32 v43, v43, s48, v146
	ds_read_b128 v[58:61], v234 offset:27712
	s_waitcnt lgkmcnt(3)
	v_mfma_f32_16x16x32_bf16 v[6:9], v[62:65], v[138:141], v[6:9]
	v_fma_f32 v44, v44, s48, v146
	v_fma_f32 v45, v45, s48, v146
	ds_read_b128 v[62:65], v234 offset:30016
	s_waitcnt lgkmcnt(3)
	v_mfma_f32_16x16x32_bf16 v[10:13], v[50:53], v[138:141], v[10:13]
	v_fma_f32 v46, v46, s48, v146
	v_fma_f32 v47, v47, s48, v146
	ds_read_b128 v[50:53], v234 offset:32320
	s_waitcnt lgkmcnt(3)
	v_mfma_f32_16x16x32_bf16 v[14:17], v[54:57], v[138:141], v[14:17]
	v_fma_f32 v48, v48, s48, v146
	v_fma_f32 v49, v49, s48, v146
	ds_read_b128 v[54:57], v234 offset:34624
	v_exp_f32_e32 v42, v42
	v_exp_f32_e32 v43, v43
	v_exp_f32_e32 v44, v44
	v_exp_f32_e32 v45, v45
	v_exp_f32_e32 v46, v46
	v_exp_f32_e32 v47, v47
	v_exp_f32_e32 v48, v48
	v_exp_f32_e32 v49, v49
	v_add_f32_e32 v34, v42, v43
	v_add_f32_e32 v35, v44, v45
	v_add_f32_e32 v34, v34, v46
	v_add_f32_e32 v35, v35, v47
	v_add_f32_e32 v34, v34, v48
	v_add_f32_e32 v35, v35, v49
	v_add_f32_e32 v34, v34, v35
	v_add_f32_e32 v129, v129, v34
	v_cvt_pk_bf16_f32 v142, v42, v43
	v_cvt_pk_bf16_f32 v143, v44, v45
	v_cvt_pk_bf16_f32 v144, v46, v47
	v_cvt_pk_bf16_f32 v145, v48, v49
	s_nop 0
	s_waitcnt lgkmcnt(3)
	v_mfma_f32_16x16x32_bf16 v[2:5], v[58:61], v[142:145], v[2:5]
	s_waitcnt lgkmcnt(2)
	v_mfma_f32_16x16x32_bf16 v[6:9], v[62:65], v[142:145], v[6:9]
	s_waitcnt lgkmcnt(1)
	v_mfma_f32_16x16x32_bf16 v[10:13], v[50:53], v[142:145], v[10:13]
	s_waitcnt lgkmcnt(0)
	v_mfma_f32_16x16x32_bf16 v[14:17], v[54:57], v[142:145], v[14:17]
	s_branch .Lsb16_end_1

.Lsb16_g1only_1:
	s_cmp_eq_u32 s76, s72
	s_cbranch_scc1 .Lsb16_g1m_1
	v_subrev_u32_e32 v146, s94, v236
	v_add_u32_e32 v146, 2, v146
	v_lshrrev_b32_e64 v146, v146, s77
	v_and_b32_e32 v146, 1, v146
	v_cmp_ne_u32_e32 vcc, 0, v146
	s_nop 1
	v_cndmask_b32_e32 v146, v213, v100, vcc
	s_waitcnt lgkmcnt(9)
	v_mfma_f32_16x16x32_bf16 v[34:37], v[50:53], v[74:77], 0
	s_waitcnt lgkmcnt(8)
	v_mfma_f32_16x16x32_bf16 v[34:37], v[54:57], v[78:81], v[34:37]
	ds_read_b128 v[50:53], v234 offset:25344
	ds_read_b128 v[54:57], v234 offset:25408
	s_waitcnt lgkmcnt(9)
	v_mfma_f32_16x16x32_bf16 v[38:41], v[58:61], v[74:77], 0
	s_waitcnt lgkmcnt(8)
	v_mfma_f32_16x16x32_bf16 v[38:41], v[62:65], v[78:81], v[38:41]
	ds_read_b128 v[58:61], v234 offset:27648
	ds_read_b128 v[62:65], v234 offset:29952
	s_waitcnt lgkmcnt(9)
	v_mfma_f32_16x16x32_bf16 v[42:45], v[138:141], v[74:77], 0
	v_fma_f32 v34, v34, s48, v146
	v_fma_f32 v35, v35, s48, v146
	s_waitcnt lgkmcnt(8)
	v_mfma_f32_16x16x32_bf16 v[42:45], v[142:145], v[78:81], v[42:45]
	v_fma_f32 v36, v36, s48, v146
	v_fma_f32 v37, v37, s48, v146
	s_waitcnt lgkmcnt(3)
	v_mfma_f32_16x16x32_bf16 v[46:49], v[50:53], v[74:77], 0
	v_fma_f32 v38, v38, s48, v146
	v_fma_f32 v39, v39, s48, v146
	s_waitcnt lgkmcnt(2)
	v_mfma_f32_16x16x32_bf16 v[46:49], v[54:57], v[78:81], v[46:49]
	v_fma_f32 v40, v40, s48, v146
	v_fma_f32 v41, v41, s48, v146
	ds_read_b128 v[50:53], v234 offset:32256
	ds_read_b128 v[54:57], v234 offset:34560
	v_exp_f32_e32 v34, v34
	v_exp_f32_e32 v35, v35
	v_exp_f32_e32 v36, v36
	v_exp_f32_e32 v37, v37
	v_exp_f32_e32 v38, v38
	v_exp_f32_e32 v39, v39
	v_exp_f32_e32 v40, v40
	v_exp_f32_e32 v41, v41
	v_add_f32_e32 v142, v34, v35
	v_add_f32_e32 v143, v36, v37
	v_add_f32_e32 v142, v142, v38
	v_add_f32_e32 v143, v143, v39
	v_add_f32_e32 v142, v142, v40
	v_add_f32_e32 v143, v143, v41
	v_add_f32_e32 v142, v142, v143
	v_add_f32_e32 v235, v235, v142
	v_cvt_pk_bf16_f32 v138, v34, v35
	v_cvt_pk_bf16_f32 v139, v36, v37
	v_cvt_pk_bf16_f32 v140, v38, v39
	v_cvt_pk_bf16_f32 v141, v40, v41
	s_nop 0
	s_waitcnt lgkmcnt(3)
	v_mfma_f32_16x16x32_bf16 v[18:21], v[58:61], v[138:141], v[18:21]
	v_fma_f32 v42, v42, s48, v146
	v_fma_f32 v43, v43, s48, v146
	ds_read_b128 v[58:61], v234 offset:27712
	s_waitcnt lgkmcnt(3)
	v_mfma_f32_16x16x32_bf16 v[22:25], v[62:65], v[138:141], v[22:25]
	v_fma_f32 v44, v44, s48, v146
	v_fma_f32 v45, v45, s48, v146
	ds_read_b128 v[62:65], v234 offset:30016
	s_waitcnt lgkmcnt(3)
	v_mfma_f32_16x16x32_bf16 v[26:29], v[50:53], v[138:141], v[26:29]
	v_fma_f32 v46, v46, s48, v146
	v_fma_f32 v47, v47, s48, v146
	ds_read_b128 v[50:53], v234 offset:32320
	s_waitcnt lgkmcnt(3)
	v_mfma_f32_16x16x32_bf16 v[30:33], v[54:57], v[138:141], v[30:33]
	v_fma_f32 v48, v48, s48, v146
	v_fma_f32 v49, v49, s48, v146
	ds_read_b128 v[54:57], v234 offset:34624
	v_exp_f32_e32 v42, v42
	v_exp_f32_e32 v43, v43
	v_exp_f32_e32 v44, v44
	v_exp_f32_e32 v45, v45
	v_exp_f32_e32 v46, v46
	v_exp_f32_e32 v47, v47
	v_exp_f32_e32 v48, v48
	v_exp_f32_e32 v49, v49
	v_add_f32_e32 v34, v42, v43
	v_add_f32_e32 v35, v44, v45
	v_add_f32_e32 v34, v34, v46
	v_add_f32_e32 v35, v35, v47
	v_add_f32_e32 v34, v34, v48
	v_add_f32_e32 v35, v35, v49
	v_add_f32_e32 v34, v34, v35
	v_add_f32_e32 v235, v235, v34
	v_cvt_pk_bf16_f32 v142, v42, v43
	v_cvt_pk_bf16_f32 v143, v44, v45
	v_cvt_pk_bf16_f32 v144, v46, v47
	v_cvt_pk_bf16_f32 v145, v48, v49
	s_nop 0
	s_waitcnt lgkmcnt(3)
	v_mfma_f32_16x16x32_bf16 v[18:21], v[58:61], v[142:145], v[18:21]
	s_waitcnt lgkmcnt(2)
	v_mfma_f32_16x16x32_bf16 v[22:25], v[62:65], v[142:145], v[22:25]
	s_waitcnt lgkmcnt(1)
	v_mfma_f32_16x16x32_bf16 v[26:29], v[50:53], v[142:145], v[26:29]
	s_waitcnt lgkmcnt(0)
	v_mfma_f32_16x16x32_bf16 v[30:33], v[54:57], v[142:145], v[30:33]
	s_branch .Lsb16_end_1
